# S5 pass 3 output block: LDS reads issued together with counted waits, store addresses formed under the MFMAs, the four GELU chains interleaved stage by stage (same operations per element)
# speedup vs baseline: 1.0009x; 1.0009x over previous
.LBB0_982:
	s_waitcnt vmcnt(4)
	v_mov_b32_e32 v50, v134
	v_mov_b32_e32 v51, v135
	v_mov_b32_e32 v52, v136
	v_mov_b32_e32 v53, v137
	s_and_saveexec_b64 s[2:3], s[4:5]
	global_load_dwordx4 v[134:137], v[130:131], off
	s_or_b64 exec, exec, s[2:3]
	v_add_co_u32_e32 v130, vcc, 0x4000, v130
	s_nop 1
	v_addc_co_u32_e32 v131, vcc, 0, v131, vcc
	v_mfma_f32_16x16x32_bf16 v[72:75], v[50:53], v[4:7], 0
	v_mfma_f32_16x16x32_bf16 v[76:79], v[50:53], v[0:3], 0
	s_nop 7
	ds_write2_b32 v68, v72, v76 offset1:16
	ds_write2_b32 v68, v73, v77 offset0:132 offset1:148
	ds_write2_b32 v71, v74, v78 offset0:8 offset1:24
	ds_write2_b32 v71, v75, v79 offset0:140 offset1:156
	v_mfma_f32_16x16x32_bf16 v[72:75], v[50:53], v[12:15], 0
	v_mfma_f32_16x16x32_bf16 v[76:79], v[50:53], v[8:11], 0
	s_nop 7
	ds_write2_b32 v68, v72, v76 offset0:32 offset1:48
	ds_write2_b32 v68, v73, v77 offset0:164 offset1:180
	ds_write2_b32 v71, v74, v78 offset0:40 offset1:56
	ds_write2_b32 v71, v75, v79 offset0:172 offset1:188
	v_mfma_f32_16x16x32_bf16 v[72:75], v[50:53], v[22:25], 0
	v_mfma_f32_16x16x32_bf16 v[76:79], v[50:53], v[18:21], 0
	s_nop 7
	ds_write2_b32 v68, v72, v76 offset0:64 offset1:80
	ds_write2_b32 v68, v73, v77 offset0:196 offset1:212
	ds_write2_b32 v71, v74, v78 offset0:72 offset1:88
	ds_write2_b32 v71, v75, v79 offset0:204 offset1:220
	v_mfma_f32_16x16x32_bf16 v[72:75], v[50:53], v[30:33], 0
	v_mfma_f32_16x16x32_bf16 v[50:53], v[50:53], v[26:29], 0
	s_nop 7
	ds_write2_b32 v68, v72, v50 offset0:96 offset1:112
	ds_write2_b32 v68, v73, v51 offset0:228 offset1:244
	ds_write2_b32 v71, v74, v52 offset0:104 offset1:120
	ds_write2_b32 v71, v75, v53 offset0:236 offset1:252
	s_waitcnt lgkmcnt(0)
	ds_read_b32 v98, v154 offset:0
	ds_read_b32 v99, v154 offset:256
	ds_read_b32 v100, v154 offset:528
	ds_read_b32 v101, v154 offset:784
	ds_read_b32 v102, v154 offset:1056
	ds_read_b32 v103, v154 offset:1312
	ds_read_b32 v104, v154 offset:1584
	ds_read_b32 v105, v154 offset:1840
	ds_read_b32 v106, v154 offset:2112
	ds_read_b32 v107, v154 offset:2368
	ds_read_b32 v108, v154 offset:2640
	ds_read_b32 v109, v154 offset:2896
	ds_read_b32 v110, v154 offset:3168
	ds_read_b32 v111, v154 offset:3424
	v_pk_mul_f32 v[52:53], v[56:57], v[62:63]
	s_nop 0
	v_pk_fma_f32 v[72:73], v[54:55], v[62:63], v[52:53] op_sel:[0,0,1] op_sel_hi:[1,1,0] neg_lo:[0,0,1]
	s_nop 0
	s_waitcnt lgkmcnt(12)
	v_pk_add_f32 v[62:63], v[72:73], v[98:99]
	ds_read_b32 v112, v154 offset:3696
	ds_read_b32 v113, v154 offset:3952
	s_nop 0
	v_cvt_pk_bf16_f32 v138, v62, v63
	v_pk_mul_f32 v[52:53], v[56:57], v[62:63]
	s_nop 0
	v_pk_fma_f32 v[72:73], v[54:55], v[62:63], v[52:53] op_sel:[0,0,1] op_sel_hi:[1,1,0] neg_lo:[0,0,1]
	s_nop 0
	s_waitcnt lgkmcnt(12)
	v_pk_add_f32 v[62:63], v[72:73], v[100:101]
	ds_read_b32 v114, v154 offset:4224
	ds_read_b32 v115, v154 offset:4480
	s_nop 0
	v_cvt_pk_bf16_f32 v139, v62, v63
	v_pk_mul_f32 v[52:53], v[56:57], v[62:63]
	s_nop 0
	v_pk_fma_f32 v[72:73], v[54:55], v[62:63], v[52:53] op_sel:[0,0,1] op_sel_hi:[1,1,0] neg_lo:[0,0,1]
	s_nop 0
	s_waitcnt lgkmcnt(12)
	v_pk_add_f32 v[62:63], v[72:73], v[102:103]
	ds_read_b32 v116, v154 offset:4752
	ds_read_b32 v117, v154 offset:5008
	s_nop 0
	v_cvt_pk_bf16_f32 v140, v62, v63
	v_pk_mul_f32 v[52:53], v[56:57], v[62:63]
	s_nop 0
	v_pk_fma_f32 v[72:73], v[54:55], v[62:63], v[52:53] op_sel:[0,0,1] op_sel_hi:[1,1,0] neg_lo:[0,0,1]
	s_nop 0
	s_waitcnt lgkmcnt(12)
	v_pk_add_f32 v[62:63], v[72:73], v[104:105]
	ds_read_b32 v118, v154 offset:5280
	ds_read_b32 v119, v154 offset:5536
	s_nop 0
	v_cvt_pk_bf16_f32 v141, v62, v63
	v_pk_mul_f32 v[52:53], v[56:57], v[62:63]
	s_nop 0
	v_pk_fma_f32 v[72:73], v[54:55], v[62:63], v[52:53] op_sel:[0,0,1] op_sel_hi:[1,1,0] neg_lo:[0,0,1]
	s_nop 0
	s_waitcnt lgkmcnt(12)
	v_pk_add_f32 v[62:63], v[72:73], v[106:107]
	ds_read_b32 v120, v154 offset:5808
	ds_read_b32 v121, v154 offset:6064
	s_nop 0
	v_cvt_pk_bf16_f32 v142, v62, v63
	v_pk_mul_f32 v[52:53], v[56:57], v[62:63]
	s_nop 0
	v_pk_fma_f32 v[72:73], v[54:55], v[62:63], v[52:53] op_sel:[0,0,1] op_sel_hi:[1,1,0] neg_lo:[0,0,1]
	s_nop 0
	s_waitcnt lgkmcnt(12)
	v_pk_add_f32 v[62:63], v[72:73], v[108:109]
	ds_read_b32 v122, v154 offset:6336
	ds_read_b32 v123, v154 offset:6592
	s_nop 0
	v_cvt_pk_bf16_f32 v143, v62, v63
	v_pk_mul_f32 v[52:53], v[56:57], v[62:63]
	s_nop 0
	v_pk_fma_f32 v[72:73], v[54:55], v[62:63], v[52:53] op_sel:[0,0,1] op_sel_hi:[1,1,0] neg_lo:[0,0,1]
	s_nop 0
	s_waitcnt lgkmcnt(12)
	v_pk_add_f32 v[62:63], v[72:73], v[110:111]
	ds_read_b32 v124, v154 offset:6864
	ds_read_b32 v125, v154 offset:7120
	s_nop 0
	v_cvt_pk_bf16_f32 v144, v62, v63
	v_pk_mul_f32 v[52:53], v[56:57], v[62:63]
	s_nop 0
	v_pk_fma_f32 v[72:73], v[54:55], v[62:63], v[52:53] op_sel:[0,0,1] op_sel_hi:[1,1,0] neg_lo:[0,0,1]
	s_nop 0
	s_waitcnt lgkmcnt(12)
	v_pk_add_f32 v[62:63], v[72:73], v[112:113]
	ds_read_b32 v126, v154 offset:7392
	ds_read_b32 v127, v154 offset:7648
	s_nop 0
	v_cvt_pk_bf16_f32 v145, v62, v63
	v_pk_mul_f32 v[52:53], v[56:57], v[62:63]
	s_nop 0
	v_pk_fma_f32 v[72:73], v[54:55], v[62:63], v[52:53] op_sel:[0,0,1] op_sel_hi:[1,1,0] neg_lo:[0,0,1]
	s_nop 0
	s_waitcnt lgkmcnt(12)
	v_pk_add_f32 v[62:63], v[72:73], v[114:115]
	ds_read_b32 v128, v154 offset:7920
	ds_read_b32 v129, v154 offset:8176
	s_nop 0
	v_cvt_pk_bf16_f32 v146, v62, v63
	v_pk_mul_f32 v[52:53], v[56:57], v[62:63]
	s_nop 0
	v_pk_fma_f32 v[72:73], v[54:55], v[62:63], v[52:53] op_sel:[0,0,1] op_sel_hi:[1,1,0] neg_lo:[0,0,1]
	s_nop 0
	s_waitcnt lgkmcnt(12)
	v_pk_add_f32 v[62:63], v[72:73], v[116:117]
	s_nop 0
	v_cvt_pk_bf16_f32 v147, v62, v63
	v_pk_mul_f32 v[52:53], v[56:57], v[62:63]
	s_nop 0
	v_pk_fma_f32 v[72:73], v[54:55], v[62:63], v[52:53] op_sel:[0,0,1] op_sel_hi:[1,1,0] neg_lo:[0,0,1]
	s_nop 0
	s_waitcnt lgkmcnt(10)
	v_pk_add_f32 v[62:63], v[72:73], v[118:119]
	s_nop 0
	v_cvt_pk_bf16_f32 v148, v62, v63
	v_pk_mul_f32 v[52:53], v[56:57], v[62:63]
	s_nop 0
	v_pk_fma_f32 v[72:73], v[54:55], v[62:63], v[52:53] op_sel:[0,0,1] op_sel_hi:[1,1,0] neg_lo:[0,0,1]
	s_nop 0
	s_waitcnt lgkmcnt(8)
	v_pk_add_f32 v[62:63], v[72:73], v[120:121]
	s_nop 0
	v_cvt_pk_bf16_f32 v149, v62, v63
	v_pk_mul_f32 v[52:53], v[56:57], v[62:63]
	s_nop 0
	v_pk_fma_f32 v[72:73], v[54:55], v[62:63], v[52:53] op_sel:[0,0,1] op_sel_hi:[1,1,0] neg_lo:[0,0,1]
	s_nop 0
	s_waitcnt lgkmcnt(6)
	v_pk_add_f32 v[62:63], v[72:73], v[122:123]
	s_nop 0
	v_cvt_pk_bf16_f32 v150, v62, v63
	v_pk_mul_f32 v[52:53], v[56:57], v[62:63]
	s_nop 0
	v_pk_fma_f32 v[72:73], v[54:55], v[62:63], v[52:53] op_sel:[0,0,1] op_sel_hi:[1,1,0] neg_lo:[0,0,1]
	s_nop 0
	s_waitcnt lgkmcnt(4)
	v_pk_add_f32 v[62:63], v[72:73], v[124:125]
	s_nop 0
	v_cvt_pk_bf16_f32 v151, v62, v63
	v_pk_mul_f32 v[52:53], v[56:57], v[62:63]
	s_nop 0
	v_pk_fma_f32 v[72:73], v[54:55], v[62:63], v[52:53] op_sel:[0,0,1] op_sel_hi:[1,1,0] neg_lo:[0,0,1]
	s_nop 0
	s_waitcnt lgkmcnt(2)
	v_pk_add_f32 v[62:63], v[72:73], v[126:127]
	s_nop 0
	v_cvt_pk_bf16_f32 v152, v62, v63
	v_pk_mul_f32 v[52:53], v[56:57], v[62:63]
	s_nop 0
	v_pk_fma_f32 v[72:73], v[54:55], v[62:63], v[52:53] op_sel:[0,0,1] op_sel_hi:[1,1,0] neg_lo:[0,0,1]
	s_nop 0
	s_waitcnt lgkmcnt(0)
	v_pk_add_f32 v[62:63], v[72:73], v[128:129]
	s_nop 0
	v_cvt_pk_bf16_f32 v153, v62, v63
	ds_write_b32 v155, v138 offset:0
	ds_write_b32 v155, v139 offset:272
	ds_write_b32 v155, v140 offset:544
	ds_write_b32 v155, v141 offset:816
	ds_write_b32 v155, v142 offset:1088
	ds_write_b32 v155, v143 offset:1360
	ds_write_b32 v155, v144 offset:1632
	ds_write_b32 v155, v145 offset:1904
	ds_write_b32 v155, v146 offset:2176
	ds_write_b32 v155, v147 offset:2448
	ds_write_b32 v155, v148 offset:2720
	ds_write_b32 v155, v149 offset:2992
	ds_write_b32 v155, v150 offset:3264
	ds_write_b32 v155, v151 offset:3536
	ds_write_b32 v155, v152 offset:3808
	ds_write_b32 v155, v153 offset:4080
	s_waitcnt lgkmcnt(0)
	ds_read_b128 v[98:101], v69 offset:49152
	ds_read_b128 v[102:105], v69 offset:49216
	ds_read_b128 v[106:109], v69 offset:49280
	ds_read_b128 v[110:113], v69 offset:49344
	v_lshl_or_b32 v74, s35, 4, v87
	v_lshl_add_u32 v114, v74, 6, v88
	v_or_b32_e32 v120, 1, v74
	v_lshl_add_u32 v115, v120, 6, v88
	v_or_b32_e32 v122, 2, v74
	v_lshl_add_u32 v116, v122, 6, v88
	v_or_b32_e32 v124, 3, v74
	v_lshl_add_u32 v117, v124, 6, v88
	ds_read_b32 v114, v114 offset:16384
	ds_read_b32 v115, v115 offset:16384
	ds_read_b32 v116, v116 offset:16384
	ds_read_b32 v117, v117 offset:16384
	s_add_i32 s35, s35, 1
	s_cmp_eq_u32 s35, 4
	s_waitcnt lgkmcnt(7)
	v_mfma_f32_16x16x32_bf16 v[50:53], v[98:101], v[34:37], 0
	s_waitcnt lgkmcnt(6)
	v_mfma_f32_16x16x32_bf16 v[50:53], v[102:105], v[38:41], v[50:53]
	s_waitcnt lgkmcnt(5)
	v_mfma_f32_16x16x32_bf16 v[50:53], v[106:109], v[42:45], v[50:53]
	s_waitcnt lgkmcnt(4)
	v_mfma_f32_16x16x32_bf16 v[50:53], v[110:113], v[46:49], v[50:53]
	v_or_b32_e32 v118, s25, v74
	v_or_b32_e32 v120, s25, v120
	v_or_b32_e32 v122, s25, v122
	v_or_b32_e32 v124, s25, v124
	v_ashrrev_i32_e32 v119, 31, v118
	v_ashrrev_i32_e32 v121, 31, v120
	v_ashrrev_i32_e32 v123, 31, v122
	v_ashrrev_i32_e32 v125, 31, v124
	v_lshlrev_b64 v[118:119], 10, v[118:119]
	v_lshlrev_b64 v[120:121], 10, v[120:121]
	v_lshlrev_b64 v[122:123], 10, v[122:123]
	v_lshlrev_b64 v[124:125], 10, v[124:125]
	v_lshl_add_u64 v[118:119], v[60:61], 0, v[118:119]
	v_lshl_add_u64 v[120:121], v[60:61], 0, v[120:121]
	v_lshl_add_u64 v[122:123], v[60:61], 0, v[122:123]
	v_lshl_add_u64 v[124:125], v[60:61], 0, v[124:125]
	s_waitcnt lgkmcnt(0)
	v_fma_f32 v50, v66, v114, v50
	v_fma_f32 v51, v66, v115, v51
	v_fma_f32 v52, v66, v116, v52
	v_fma_f32 v53, v66, v117, v53
	v_mul_f32_e32 v126, 0x3d372713, v50
	v_mul_f32_e32 v127, 0x3d372713, v51
	v_mul_f32_e32 v128, 0x3d372713, v52
	v_mul_f32_e32 v129, 0x3d372713, v53
	v_mul_f32_e32 v126, v50, v126
	v_mul_f32_e32 v127, v51, v127
	v_mul_f32_e32 v128, v52, v128
	v_mul_f32_e32 v129, v53, v129
	v_fma_f32 v126, v50, v126, v50
	v_fma_f32 v127, v51, v127, v51
	v_fma_f32 v128, v52, v128, v52
	v_fma_f32 v129, v53, v129, v53
	v_mul_f32_e32 v126, 0x3f4c422a, v126
	v_mul_f32_e32 v127, 0x3f4c422a, v127
	v_mul_f32_e32 v128, 0x3f4c422a, v128
	v_mul_f32_e32 v129, 0x3f4c422a, v129
	v_add_f32_e32 v126, v126, v126
	v_add_f32_e32 v127, v127, v127
	v_add_f32_e32 v128, v128, v128
	v_add_f32_e32 v129, v129, v129
	v_mul_f32_e32 v126, 0x3fb8aa3b, v126
	v_mul_f32_e32 v127, 0x3fb8aa3b, v127
	v_mul_f32_e32 v128, 0x3fb8aa3b, v128
	v_mul_f32_e32 v129, 0x3fb8aa3b, v129
	v_exp_f32_e32 v126, v126
	v_exp_f32_e32 v127, v127
	v_exp_f32_e32 v128, v128
	v_exp_f32_e32 v129, v129
	v_mul_f32_e32 v98, 0.5, v50
	v_mul_f32_e32 v99, 0.5, v51
	v_mul_f32_e32 v100, 0.5, v52
	v_mul_f32_e32 v101, 0.5, v53
	v_add_f32_e32 v126, 1.0, v126
	v_add_f32_e32 v127, 1.0, v127
	v_add_f32_e32 v128, 1.0, v128
	v_add_f32_e32 v129, 1.0, v129
	v_rcp_f32_e32 v126, v126
	v_rcp_f32_e32 v127, v127
	v_rcp_f32_e32 v128, v128
	v_rcp_f32_e32 v129, v129
	v_fma_f32 v126, v126, -2.0, 1.0
	v_fma_f32 v127, v127, -2.0, 1.0
	v_fma_f32 v128, v128, -2.0, 1.0
	v_fma_f32 v129, v129, -2.0, 1.0
	v_add_f32_e32 v126, 1.0, v126
	v_add_f32_e32 v127, 1.0, v127
	v_add_f32_e32 v128, 1.0, v128
	v_add_f32_e32 v129, 1.0, v129
	v_mul_f32_e32 v126, v98, v126
	v_mul_f32_e32 v127, v99, v127
	v_mul_f32_e32 v128, v100, v128
	v_mul_f32_e32 v129, v101, v129
	v_cvt_pk_bf16_f32 v126, v126, 0
	v_cvt_pk_bf16_f32 v127, v127, 0
	v_cvt_pk_bf16_f32 v128, v128, 0
	v_cvt_pk_bf16_f32 v129, v129, 0
	global_store_short v[118:119], v126, off
	global_store_short v[120:121], v127, off
	global_store_short v[122:123], v128, off
	global_store_short v[124:125], v129, off
	s_waitcnt lgkmcnt(0)
	s_cbranch_scc0 .LBB0_982
	s_add_i32 s21, s21, 1
	s_cmp_eq_u32 s21, 4
	s_cbranch_scc0 .LBB0_981
	s_add_i32 s34, s34, s59
	s_cmpk_lt_i32 s34, 0x200
	s_barrier
	s_cbranch_scc1 .LBB0_944
	v_readlane_b32 s0, v253, 38
	v_readlane_b32 s8, v253, 46
	v_readlane_b32 s14, v253, 52
	v_readlane_b32 s9, v253, 47
	v_readlane_b32 s15, v253, 53
	s_add_u32 s8, s14, 0x34e00000
	v_readlane_b32 s10, v253, 48
	s_addc_u32 s9, s15, 0
	v_readlane_b32 s11, v253, 49
	v_readlane_b32 s12, v253, 50
	v_readlane_b32 s13, v253, 51
	s_add_u32 s10, s14, 0x9a00800
	s_addc_u32 s11, s15, 0
	v_readlane_b32 s12, v253, 6
	s_mov_b32 s13, s58
	v_readlane_b32 s1, v253, 39
	v_readlane_b32 s2, v253, 40
	v_readlane_b32 s3, v253, 41
	v_readlane_b32 s4, v253, 42
	v_readlane_b32 s5, v253, 43
	v_readlane_b32 s6, v253, 44
	v_readlane_b32 s7, v253, 45
